# code placement: s_nop pads in cold spots so the four GEMM K-loop heads and the attention/B-out code return to the baseline byte phase mod 64 (B-in loop head was at 4 mod 8)
# speedup vs baseline: 1.0015x; 1.0015x over previous
.LBB0_272:
	s_mov_b32 s98, 0
	s_nop 0
	s_nop 0
	s_nop 0
	s_nop 0
	s_nop 0
	s_nop 0
	s_nop 0
	s_nop 0
	s_nop 0
	s_nop 0
	s_nop 0
	s_nop 0
	s_and_b64 s[8:9], s[52:53], exec
	s_cselect_b32 s8, s17, 0x8000000
	s_add_u32 s48, s84, s8
	s_addc_u32 s49, s85, 0
	s_and_b64 s[8:9], s[52:53], exec
	s_cselect_b32 s8, 0x8000000, s17
	s_add_u32 s50, s84, s8
	s_addc_u32 s51, s85, 0
	s_lshl_b32 s30, s64, 14
	s_lshl_b64 s[8:9], s[30:31], 2
	v_readlane_b32 s10, v242, 3
	v_readlane_b32 s11, v242, 4
	s_add_u32 s42, s10, s8
	v_mov_b32_e32 v5, v1
	s_addc_u32 s43, s11, s9
	s_andn2_b64 vcc, exec, s[0:1]
	v_readfirstlane_b32 s8, v5
	s_cbranch_vccnz .LBB0_330
	v_bfe_i32 v3, v5, 27, 1
	v_lshlrev_b32_e32 v6, 4, v5
	v_lshrrev_b32_e32 v3, 22, v3
	v_ashrrev_i32_e32 v2, 31, v5
	v_add_u32_e32 v3, v6, v3
	v_lshrrev_b32_e32 v2, 26, v2
	v_and_b32_e32 v3, 0xfffffc00, v3
	v_add_u32_e32 v2, v5, v2
	v_sub_u32_e32 v3, v6, v3
	v_ashrrev_i32_e32 v2, 6, v2
	v_lshrrev_b32_e32 v4, 4, v3
	v_bitop3_b32 v4, v4, v3, 32 bitop3:0x6c
	v_lshlrev_b32_e32 v3, 3, v2
	v_and_b32_e32 v7, -16, v3
	v_ashrrev_i32_e32 v3, 31, v4
	v_lshrrev_b32_e32 v3, 26, v3
	v_add_u32_e32 v8, v4, v3
	v_ashrrev_i32_e32 v3, 6, v8
	v_and_b32_e32 v8, 0xc0, v8
	v_sub_u32_e32 v4, v4, v8
	v_lshlrev_b32_e32 v9, 5, v2
	v_ashrrev_i16_sdwa v4, v193, sext(v4) dst_sel:DWORD dst_unused:UNUSED_PAD src0_sel:DWORD src1_sel:BYTE_0
	v_and_b32_e32 v9, 32, v9
	v_bfe_i32 v4, v4, 0, 16
	v_add_u32_e32 v7, v3, v7
	v_and_b32_e32 v11, 3, v3
	v_add_lshl_u32 v9, v9, v4, 1
	v_lshlrev_b32_e32 v8, 1, v7
	v_lshrrev_b32_e32 v10, 2, v7
	v_and_or_b32 v11, v7, s25, v11
	v_lshl_add_u32 v130, v7, 12, v9
	v_add_u32_e32 v7, 0x2000, v6
	v_ashrrev_i32_e32 v6, 31, v7
	v_lshrrev_b32_e32 v6, 22, v6
	v_and_b32_e32 v8, 24, v8
	v_and_b32_e32 v10, 4, v10
	v_add_u32_e32 v6, v7, v6
	v_or3_b32 v8, v11, v10, v8
	v_ashrrev_i32_e32 v6, 10, v6
	v_lshl_add_u32 v132, v8, 12, v9
	v_mul_i32_i24_e32 v8, 0x400, v6
	v_sub_u32_e32 v7, v7, v8
	v_lshrrev_b32_e32 v8, 4, v7
	s_and_b64 s[10:11], s[52:53], exec
	v_bitop3_b32 v8, v8, v7, 32 bitop3:0x6c
	v_lshlrev_b32_e32 v7, 3, v6
	s_cselect_b32 s9, 0, 0x1000000
	v_and_b32_e32 v9, -16, v7
	v_ashrrev_i32_e32 v7, 31, v8
	s_add_u32 s30, s94, s9
	v_lshrrev_b32_e32 v7, 26, v7
	s_addc_u32 s65, s95, 0
	v_add_u32_e32 v10, v8, v7
	s_ashr_i32 s12, s8, 6
	s_ashr_i32 s9, s8, 8
	v_ashrrev_i32_e32 v7, 6, v10
	v_and_b32_e32 v10, 0xc0, v10
	s_lshl_b32 s80, s12, 10
	v_add_u32_e32 v9, v7, v9
	v_sub_u32_e32 v8, v8, v10
	s_add_u32 s10, s30, s26
	v_lshlrev_b32_e32 v11, 5, v6
	v_ashrrev_i16_sdwa v8, v193, sext(v8) dst_sel:DWORD dst_unused:UNUSED_PAD src0_sel:DWORD src1_sel:BYTE_0
	v_lshlrev_b32_e32 v10, 1, v9
	v_lshrrev_b32_e32 v12, 2, v9
	v_and_b32_e32 v13, 3, v7
	s_addc_u32 s11, s65, s27
	s_add_i32 s81, s80, 0
	v_and_b32_e32 v11, 32, v11
	v_bfe_i32 v8, v8, 0, 16
	v_and_b32_e32 v10, 24, v10
	v_and_b32_e32 v12, 4, v12
	v_and_or_b32 v13, v9, s25, v13
	s_add_i32 m0, s81, 0x10000
	v_or3_b32 v10, v13, v12, v10
	v_add_lshl_u32 v11, v11, v8, 1
	global_load_lds_dwordx4 v132, s[10:11]
	s_add_i32 m0, s81, 0x12000
	v_lshl_add_u32 v136, v10, 12, v11
	s_add_u32 s28, s10, 0x80000
	global_load_lds_dwordx4 v136, s[10:11]
	s_addc_u32 s29, s11, 0
	s_add_i32 m0, s81, 0x14000
	v_lshl_add_u32 v134, v9, 12, v11
	global_load_lds_dwordx4 v132, s[28:29]
	s_add_i32 m0, s81, 0x16000
	s_add_u32 s60, s48, s18
	s_addc_u32 s61, s49, s19
	s_add_i32 s82, s81, 0x2000
	global_load_lds_dwordx4 v136, s[28:29]
	s_mov_b32 m0, s81
	s_add_u32 s28, s60, 0x80000
	global_load_lds_dwordx4 v130, s[60:61]
	s_mov_b32 m0, s82
	s_addc_u32 s29, s61, 0
	s_add_i32 s83, s81, 0x4000
	global_load_lds_dwordx4 v134, s[60:61]
	s_mov_b32 m0, s83
	s_add_i32 s84, s81, 0x6000
	global_load_lds_dwordx4 v130, s[28:29]
	s_mov_b32 m0, s84
	s_cmp_eq_u32 s9, 1
	global_load_lds_dwordx4 v134, s[28:29]
	s_cselect_b64 s[54:55], -1, 0
	s_cmp_lg_u32 s9, 1
	s_cbranch_scc1 .LBB0_275
	s_barrier

.LBB0_382:
	s_or_b64 exec, exec, s[8:9]
	v_mov_b32_e32 v10, v1
	s_waitcnt lgkmcnt(0)
	s_barrier
	s_cmp_lg_u32 s74, 0x10000
	s_cbranch_scc1 .Lpool_generic
	s_nop 0
	s_nop 0
	s_nop 0
	s_nop 0
	s_nop 0
	s_nop 0
	s_nop 0
	s_nop 0
	s_xor_b64 s[36:37], s[52:53], -1
	v_add_u32_e32 v3, s75, v1
	v_add_u32_e32 v3, s76, v3
	v_lshrrev_b32_e32 v3, 8, v3
	v_and_b32_e32 v2, 0xff, v1
	v_lshlrev_b32_e32 v2, 4, v2
	v_lshl_or_b32 v2, v3, 17, v2
	s_nop 0
	v_readfirstlane_b32 s100, v3
	v_readfirstlane_b32 s101, v1
	v_and_b32_e32 v3, 0xff, v1
	v_lshlrev_b32_e32 v3, 5, v3
	s_lshl_b32 s30, s64, 13
	s_add_u32 s98, s44, s30
	s_addc_u32 s99, s45, 0
	global_load_dwordx4 v[108:111], v3, s[98:99]
	global_load_dwordx4 v[112:115], v3, s[98:99] offset:16
	s_bfe_u32 s101, s101, 0x20006
	s_add_u32 s39, s101, 1
	s_lshl_b32 s38, s39, 23
	s_sub_u32 s38, 0x3f800000, s38
	s_lshl_b32 s101, 2, s101
	s_sub_u32 s101, s101, 1
	s_add_u32 s8, s84, 0xc000000
	s_addc_u32 s9, s85, 0
	s_mov_b64 s[10:11], s[50:51]
	s_add_u32 s12, s84, 0x14000000
	s_addc_u32 s13, s85, 0
	s_lshl_b32 s39, s101, 12
	s_sub_u32 s40, s8, s39
	s_subb_u32 s41, s9, 0
	s_and_b32 s100, s100, 0x7f
	s_cmp_eq_u32 s100, 0
	s_cselect_b32 s30, s101, 0
	s_mov_b32 s100, 0
	v_mov_b32_e32 v100, 0
	v_mov_b32_e32 v101, 0
	v_mov_b32_e32 v102, 0
	v_mov_b32_e32 v103, 0
	v_mov_b32_e32 v104, 0
	v_mov_b32_e32 v105, 0
	v_mov_b32_e32 v106, 0
	v_mov_b32_e32 v107, 0
	s_cmp_lg_u32 s30, 0
	s_cbranch_scc1 .Lpool_lb_done
	s_sub_u32 s98, s8, 0x1000
	s_subb_u32 s99, s9, 0
	global_load_dwordx4 v[36:39], v2, s[98:99]
	s_cmp_lt_u32 s101, 2
	s_cbranch_scc1 .Lpool_lb_issued
	s_sub_u32 s98, s8, 0x2000
	s_subb_u32 s99, s9, 0
	global_load_dwordx4 v[40:43], v2, s[98:99]
	s_sub_u32 s98, s8, 0x3000
	s_subb_u32 s99, s9, 0
	global_load_dwordx4 v[44:47], v2, s[98:99]
	s_cmp_lt_u32 s101, 4
	s_cbranch_scc1 .Lpool_lb_issued
	s_sub_u32 s98, s8, 0x4000
	s_subb_u32 s99, s9, 0
	global_load_dwordx4 v[48:51], v2, s[98:99]
	s_sub_u32 s98, s8, 0x5000
	s_subb_u32 s99, s9, 0
	global_load_dwordx4 v[52:55], v2, s[98:99]
	s_sub_u32 s98, s8, 0x6000
	s_subb_u32 s99, s9, 0
	global_load_dwordx4 v[56:59], v2, s[98:99]
	s_sub_u32 s98, s8, 0x7000
	s_subb_u32 s99, s9, 0
	global_load_dwordx4 v[60:63], v2, s[98:99]
	s_cmp_lt_u32 s101, 8
	s_cbranch_scc1 .Lpool_lb_issued
	s_sub_u32 s98, s8, 0x8000
	s_subb_u32 s99, s9, 0
	global_load_dwordx4 v[64:67], v2, s[98:99]
	s_sub_u32 s98, s8, 0x9000
	s_subb_u32 s99, s9, 0
	global_load_dwordx4 v[68:71], v2, s[98:99]
	s_sub_u32 s98, s8, 0xa000
	s_subb_u32 s99, s9, 0
	global_load_dwordx4 v[72:75], v2, s[98:99]
	s_sub_u32 s98, s8, 0xb000
	s_subb_u32 s99, s9, 0
	global_load_dwordx4 v[76:79], v2, s[98:99]
	s_sub_u32 s98, s8, 0xc000
	s_subb_u32 s99, s9, 0
	global_load_dwordx4 v[80:83], v2, s[98:99]
	s_sub_u32 s98, s8, 0xd000
	s_subb_u32 s99, s9, 0
	global_load_dwordx4 v[84:87], v2, s[98:99]
	s_sub_u32 s98, s8, 0xe000
	s_subb_u32 s99, s9, 0
	global_load_dwordx4 v[88:91], v2, s[98:99]
	s_sub_u32 s98, s8, 0xf000
	s_subb_u32 s99, s9, 0
	global_load_dwordx4 v[92:95], v2, s[98:99]

.LBB0_567:
	s_mov_b32 s98, 0
	s_nop 0
	s_nop 0
	s_nop 0
	s_nop 0
	s_nop 0
	s_nop 0
	s_nop 0
	s_nop 0
	s_nop 0
	s_nop 0
	s_nop 0
	s_nop 0
	s_nop 0
	s_nop 0
	s_nop 0
	s_and_b64 s[8:9], s[30:31], exec
	s_cselect_b32 s12, 48, 32
	s_lshl_b32 s20, s12, 5
	v_mov_b32_e32 v2, v1
	s_cmp_lt_i32 s88, s20
	s_cselect_b64 s[8:9], -1, 0
	s_cmp_ge_i32 s88, s20
	v_readfirstlane_b32 s13, v2
	s_cbranch_scc1 .LBB0_569
	s_lshl_b32 s10, s12, 3
	v_cvt_f32_u32_e32 v4, s10
	s_lshl_b32 s11, s12, 2
	v_readlane_b32 s14, v240, 1
	s_or_b32 s11, s11, s14
	v_rcp_iflag_f32_e32 v4, v4
	s_sub_i32 s14, 0, s10
	v_readlane_b32 s15, v241, 15
	s_mul_i32 s11, s11, s15
	v_mul_f32_e32 v4, 0x4f7ffffe, v4
	v_cvt_u32_f32_e32 v4, v4
	v_readlane_b32 s15, v241, 16
	s_add_i32 s11, s11, s15
	s_abs_i32 s24, s11
	v_readfirstlane_b32 s25, v4
	s_mul_i32 s14, s14, s25
	s_mul_hi_u32 s14, s25, s14
	s_add_i32 s25, s25, s14
	s_mul_hi_u32 s14, s24, s25
	s_mul_i32 s25, s14, s10
	s_sub_i32 s24, s24, s25
	s_ashr_i32 s15, s11, 31
	s_add_i32 s26, s14, 1
	s_sub_i32 s25, s24, s10
	s_cmp_ge_u32 s24, s10
	s_cselect_b32 s14, s26, s14
	s_cselect_b32 s24, s25, s24
	s_add_i32 s25, s14, 1
	s_cmp_ge_u32 s24, s10
	s_cselect_b32 s14, s25, s14
	s_xor_b32 s14, s14, s15
	s_sub_i32 s14, s14, s15
	s_lshl_b32 s24, s14, 3
	s_sub_i32 s15, 32, s24
	s_min_i32 s25, s15, 8
	s_mul_i32 s14, s14, s10
	s_sext_i32_i16 s10, s25
	v_cvt_f32_i32_e32 v4, s10
	s_sub_i32 s14, s11, s14
	s_sext_i32_i16 s11, s14
	v_cvt_f32_i32_e32 v5, s11
	v_rcp_iflag_f32_e32 v6, v4
	s_xor_b32 s10, s11, s10
	s_ashr_i32 s10, s10, 30
	s_or_b32 s15, s10, 1
	v_mul_f32_e32 v6, v5, v6
	v_trunc_f32_e32 v6, v6
	v_fma_f32 v5, -v6, v4, v5
	v_cvt_i32_f32_e32 v6, v6
	v_cmp_ge_f32_e64 s[10:11], |v5|, |v4|
	s_and_b64 s[10:11], s[10:11], exec
	s_cselect_b32 s10, s15, 0
	v_readfirstlane_b32 s11, v6
	s_add_i32 s10, s11, s10
	s_sext_i32_i16 s15, s10
	s_mul_i32 s10, s10, s25
	s_sub_i32 s10, s14, s10
	s_sext_i32_i16 s10, s10
	s_add_i32 s14, s24, s10

.LBB0_703:
	s_or_b64 exec, exec, s[0:1]
	v_mov_b32_e32 v54, v1
	s_waitcnt lgkmcnt(0)
	s_barrier
	s_nop 0
	s_nop 0
	s_nop 0
	s_nop 0
	s_nop 0
	s_nop 0
	s_nop 0
	s_nop 0
	s_nop 0
	s_nop 0
	s_nop 0
	s_nop 0
	s_andn2_b64 vcc, exec, s[96:97]
	v_readfirstlane_b32 s8, v54
	s_barrier
	s_cbranch_vccnz .LBB0_729
	v_lshlrev_b32_e32 v2, 4, v54
	v_readlane_b32 s10, v241, 50
	v_and_b32_e32 v107, 0xffffff00, v2
	v_readlane_b32 s11, v241, 51
	v_and_b32_e32 v106, 0xf0, v2
	v_readlane_b32 s0, v241, 48
	v_add_u32_e32 v108, 0xffff8000, v107
	v_cndmask_b32_e64 v2, 0, 1, s[10:11]
	s_waitcnt vmcnt(17)
	v_or_b32_e32 v46, s0, v106
	v_add_u32_e32 v47, s93, v108
	v_cmp_ne_u32_e64 s[0:1], 1, v2
	s_andn2_b64 vcc, exec, s[10:11]
	s_cbranch_vccnz .LBB0_709
	v_lshl_add_u32 v2, v47, s83, v46
	global_load_dwordx4 v[6:9], v2, s[70:71]
	s_and_b64 vcc, exec, s[0:1]
	s_cbranch_vccnz .LBB0_710
